# 768 weight-transpose items (w_gate, w_up, part of w_down; first used in phase 7) moved from phase 0 to the 256 workgroups that are idle in phase 5
# speedup vs baseline: 1.1802x; 1.0069x over previous
.Lp5_idle:
	s_cmpk_eq_i32 s72, 0x200
	s_cbranch_scc0 .Lp5_idle_none
	s_add_u32 s46, s12, 8
	s_addc_u32 s47, s13, 0
	s_add_i32 s50, s60, 0x128
	s_movk_i32 s51, 0x100
	s_movk_i32 s52, 0x527
	s_mov_b32 s53, 0
	s_branch .Ltramp_p0b

.LBB0_362:
	s_andn2_b64 vcc, exec, s[40:41]
	s_cbranch_vccnz .Ltramp7a
	v_readlane_b32 s20, v209, 10
	v_readlane_b32 s21, v209, 11
	s_andn2_b64 vcc, exec, s[20:21]
	s_cbranch_vccnz .Ltramp7a
	s_add_u32 s46, s12, 8
	s_addc_u32 s47, s13, 0
	s_mov_b32 s50, s60
	s_mov_b32 s51, s72
	s_movk_i32 s52, 0xaf0
	s_mov_b32 s53, 0
	s_cmpk_eq_i32 s72, 0x200
	s_cbranch_scc0 .Lp0_head
	s_movk_i32 s52, 0x7f0
	s_movk_i32 s53, 0x300
	s_branch .Lp0_head
.Ltramp7b:
	s_branch .Ltramp7a
.Ltramp_p0b:
	s_branch .Lp0_head

.LBB0_488:
	s_add_i32 s50, s50, s51
	s_cmp_gt_i32 s50, s52
	s_cbranch_scc1 .Ltramp7b
.Lp0_head:
	s_mov_b32 s8, s50
	s_cmpk_lt_i32 s50, 0x228
	s_cbranch_scc1 .LBB0_489
	s_add_i32 s8, s50, s53
